# GEMM loop heads aligned to 128 bytes instead of 64 (placement variant of v112)
# speedup vs baseline: 1.0039x; 1.0039x over previous
.LBB0_315:
	s_ashr_i32 s65, s64, 31
	s_lshl_b64 s[0:1], s[64:65], 20
	s_add_u32 s70, s20, s0
	s_addc_u32 s71, s21, s1
	s_and_b64 s[0:1], s[8:9], exec
	s_cselect_b32 s0, s71, s75
	s_cselect_b32 s1, s70, s74
	s_add_u32 s8, s76, 0x80080
	s_addc_u32 s9, s77, 0
	s_add_u32 s12, s74, 0x100
	v_mov_b32_e32 v0, 0
	s_addc_u32 s24, s75, 0
	s_mov_b32 s25, -2
	v_mov_b32_e32 v1, v0
	v_mov_b32_e32 v2, v0
	v_mov_b32_e32 v3, v0
	v_mov_b32_e32 v4, v0
	v_mov_b32_e32 v5, v0
	v_mov_b32_e32 v6, v0
	v_mov_b32_e32 v7, v0
	v_mov_b32_e32 v8, v0
	v_mov_b32_e32 v9, v0
	v_mov_b32_e32 v10, v0
	v_mov_b32_e32 v11, v0
	v_mov_b32_e32 v12, v0
	v_mov_b32_e32 v13, v0
	v_mov_b32_e32 v14, v0
	v_mov_b32_e32 v15, v0
	v_mov_b32_e32 v20, v0
	v_mov_b32_e32 v21, v0
	v_mov_b32_e32 v22, v0
	v_mov_b32_e32 v23, v0
	v_mov_b32_e32 v28, v0
	v_mov_b32_e32 v29, v0
	v_mov_b32_e32 v30, v0
	v_mov_b32_e32 v31, v0
	v_mov_b32_e32 v36, v0
	v_mov_b32_e32 v37, v0
	v_mov_b32_e32 v38, v0
	v_mov_b32_e32 v39, v0
	v_mov_b32_e32 v44, v0
	v_mov_b32_e32 v45, v0
	v_mov_b32_e32 v46, v0
	v_mov_b32_e32 v47, v0
	v_mov_b32_e32 v16, v0
	v_mov_b32_e32 v17, v0
	v_mov_b32_e32 v18, v0
	v_mov_b32_e32 v19, v0
	v_mov_b32_e32 v24, v0
	v_mov_b32_e32 v25, v0
	v_mov_b32_e32 v26, v0
	v_mov_b32_e32 v27, v0
	v_mov_b32_e32 v32, v0
	v_mov_b32_e32 v33, v0
	v_mov_b32_e32 v34, v0
	v_mov_b32_e32 v35, v0
	v_mov_b32_e32 v40, v0
	v_mov_b32_e32 v41, v0
	v_mov_b32_e32 v42, v0
	v_mov_b32_e32 v43, v0
	v_mov_b32_e32 v48, v0
	v_mov_b32_e32 v49, v0
	v_mov_b32_e32 v50, v0
	v_mov_b32_e32 v51, v0
	v_mov_b32_e32 v52, v0
	v_mov_b32_e32 v53, v0
	v_mov_b32_e32 v54, v0
	v_mov_b32_e32 v55, v0
	v_mov_b32_e32 v56, v0
	v_mov_b32_e32 v57, v0
	v_mov_b32_e32 v58, v0
	v_mov_b32_e32 v59, v0
	v_mov_b32_e32 v60, v0
	v_mov_b32_e32 v61, v0
	v_mov_b32_e32 v62, v0
	v_mov_b32_e32 v63, v0
	v_mov_b32_e32 v64, v0
	v_mov_b32_e32 v65, v0
	v_mov_b32_e32 v66, v0
	v_mov_b32_e32 v67, v0
	v_mov_b32_e32 v68, v0
	v_mov_b32_e32 v69, v0
	v_mov_b32_e32 v70, v0
	v_mov_b32_e32 v71, v0
	v_mov_b32_e32 v72, v0
	v_mov_b32_e32 v73, v0
	v_mov_b32_e32 v74, v0
	v_mov_b32_e32 v75, v0
	v_mov_b32_e32 v76, v0
	v_mov_b32_e32 v77, v0
	v_mov_b32_e32 v78, v0
	v_mov_b32_e32 v79, v0
	v_mov_b32_e32 v88, v0
	v_mov_b32_e32 v89, v0
	v_mov_b32_e32 v90, v0
	v_mov_b32_e32 v91, v0
	v_mov_b32_e32 v92, v0
	v_mov_b32_e32 v93, v0
	v_mov_b32_e32 v94, v0
	v_mov_b32_e32 v95, v0
	v_mov_b32_e32 v104, v0
	v_mov_b32_e32 v105, v0
	v_mov_b32_e32 v106, v0
	v_mov_b32_e32 v107, v0
	v_mov_b32_e32 v108, v0
	v_mov_b32_e32 v109, v0
	v_mov_b32_e32 v110, v0
	v_mov_b32_e32 v111, v0
	v_mov_b32_e32 v80, v0
	v_mov_b32_e32 v81, v0
	v_mov_b32_e32 v82, v0
	v_mov_b32_e32 v83, v0
	v_mov_b32_e32 v84, v0
	v_mov_b32_e32 v85, v0
	v_mov_b32_e32 v86, v0
	v_mov_b32_e32 v87, v0
	v_mov_b32_e32 v96, v0
	v_mov_b32_e32 v97, v0
	v_mov_b32_e32 v98, v0
	v_mov_b32_e32 v99, v0
	v_mov_b32_e32 v100, v0
	v_mov_b32_e32 v101, v0
	v_mov_b32_e32 v102, v0
	v_mov_b32_e32 v103, v0
	v_mov_b32_e32 v112, v0
	v_mov_b32_e32 v113, v0
	v_mov_b32_e32 v114, v0
	v_mov_b32_e32 v115, v0
	v_mov_b32_e32 v116, v0
	v_mov_b32_e32 v117, v0
	v_mov_b32_e32 v118, v0
	v_mov_b32_e32 v119, v0
	v_mov_b32_e32 v120, v0
	v_mov_b32_e32 v121, v0
	v_mov_b32_e32 v122, v0
	v_mov_b32_e32 v123, v0
	v_mov_b32_e32 v124, v0
	v_mov_b32_e32 v125, v0
	v_mov_b32_e32 v126, v0
	v_mov_b32_e32 v127, v0
	.p2alignl 7, 3212836864

.LBB0_849:
	s_ashr_i32 s67, s66, 31
	v_cmp_lt_i64_e32 vcc, s[0:1], v[136:137]
	s_lshl_b64 s[0:1], s[66:67], 20
	s_add_u32 s68, s8, s0
	s_addc_u32 s69, s9, s1
	s_and_b64 s[0:1], vcc, exec
	s_cselect_b32 s0, s69, s75
	s_cselect_b32 s1, s68, s74
	s_ashr_i32 s61, s60, 31
	s_lshl_b64 s[4:5], s[60:61], 20
	s_add_u32 s70, s64, s4
	s_addc_u32 s71, s65, s5
	s_and_b64 s[4:5], vcc, exec
	s_cselect_b32 s46, s71, s51
	s_cselect_b32 s47, s70, s50
	s_add_u32 s61, s50, 0x100
	v_mov_b32_e32 v0, 0
	s_addc_u32 s67, s51, 0
	s_mov_b32 s73, -2
	v_mov_b32_e32 v1, v0
	v_mov_b32_e32 v2, v0
	v_mov_b32_e32 v3, v0
	v_mov_b32_e32 v20, v0
	v_mov_b32_e32 v21, v0
	v_mov_b32_e32 v22, v0
	v_mov_b32_e32 v23, v0
	v_mov_b32_e32 v4, v0
	v_mov_b32_e32 v5, v0
	v_mov_b32_e32 v6, v0
	v_mov_b32_e32 v7, v0
	v_mov_b32_e32 v28, v0
	v_mov_b32_e32 v29, v0
	v_mov_b32_e32 v30, v0
	v_mov_b32_e32 v31, v0
	v_mov_b32_e32 v8, v0
	v_mov_b32_e32 v9, v0
	v_mov_b32_e32 v10, v0
	v_mov_b32_e32 v11, v0
	v_mov_b32_e32 v36, v0
	v_mov_b32_e32 v37, v0
	v_mov_b32_e32 v38, v0
	v_mov_b32_e32 v39, v0
	v_mov_b32_e32 v12, v0
	v_mov_b32_e32 v13, v0
	v_mov_b32_e32 v14, v0
	v_mov_b32_e32 v15, v0
	v_mov_b32_e32 v44, v0
	v_mov_b32_e32 v45, v0
	v_mov_b32_e32 v46, v0
	v_mov_b32_e32 v47, v0
	v_mov_b32_e32 v56, v0
	v_mov_b32_e32 v57, v0
	v_mov_b32_e32 v58, v0
	v_mov_b32_e32 v59, v0
	v_mov_b32_e32 v84, v0
	v_mov_b32_e32 v85, v0
	v_mov_b32_e32 v86, v0
	v_mov_b32_e32 v87, v0
	v_mov_b32_e32 v64, v0
	v_mov_b32_e32 v65, v0
	v_mov_b32_e32 v66, v0
	v_mov_b32_e32 v67, v0
	v_mov_b32_e32 v92, v0
	v_mov_b32_e32 v93, v0
	v_mov_b32_e32 v94, v0
	v_mov_b32_e32 v95, v0
	v_mov_b32_e32 v72, v0
	v_mov_b32_e32 v73, v0
	v_mov_b32_e32 v74, v0
	v_mov_b32_e32 v75, v0
	v_mov_b32_e32 v104, v0
	v_mov_b32_e32 v105, v0
	v_mov_b32_e32 v106, v0
	v_mov_b32_e32 v107, v0
	v_mov_b32_e32 v76, v0
	v_mov_b32_e32 v77, v0
	v_mov_b32_e32 v78, v0
	v_mov_b32_e32 v79, v0
	v_mov_b32_e32 v108, v0
	v_mov_b32_e32 v109, v0
	v_mov_b32_e32 v110, v0
	v_mov_b32_e32 v111, v0
	v_mov_b32_e32 v16, v0
	v_mov_b32_e32 v17, v0
	v_mov_b32_e32 v18, v0
	v_mov_b32_e32 v19, v0
	v_mov_b32_e32 v48, v0
	v_mov_b32_e32 v49, v0
	v_mov_b32_e32 v50, v0
	v_mov_b32_e32 v51, v0
	v_mov_b32_e32 v24, v0
	v_mov_b32_e32 v25, v0
	v_mov_b32_e32 v26, v0
	v_mov_b32_e32 v27, v0
	v_mov_b32_e32 v52, v0
	v_mov_b32_e32 v53, v0
	v_mov_b32_e32 v54, v0
	v_mov_b32_e32 v55, v0
	v_mov_b32_e32 v32, v0
	v_mov_b32_e32 v33, v0
	v_mov_b32_e32 v34, v0
	v_mov_b32_e32 v35, v0
	v_mov_b32_e32 v60, v0
	v_mov_b32_e32 v61, v0
	v_mov_b32_e32 v62, v0
	v_mov_b32_e32 v63, v0
	v_mov_b32_e32 v40, v0
	v_mov_b32_e32 v41, v0
	v_mov_b32_e32 v42, v0
	v_mov_b32_e32 v43, v0
	v_mov_b32_e32 v68, v0
	v_mov_b32_e32 v69, v0
	v_mov_b32_e32 v70, v0
	v_mov_b32_e32 v71, v0
	v_mov_b32_e32 v80, v0
	v_mov_b32_e32 v81, v0
	v_mov_b32_e32 v82, v0
	v_mov_b32_e32 v83, v0
	v_mov_b32_e32 v112, v0
	v_mov_b32_e32 v113, v0
	v_mov_b32_e32 v114, v0
	v_mov_b32_e32 v115, v0
	v_mov_b32_e32 v88, v0
	v_mov_b32_e32 v89, v0
	v_mov_b32_e32 v90, v0
	v_mov_b32_e32 v91, v0
	v_mov_b32_e32 v116, v0
	v_mov_b32_e32 v117, v0
	v_mov_b32_e32 v118, v0
	v_mov_b32_e32 v119, v0
	v_mov_b32_e32 v96, v0
	v_mov_b32_e32 v97, v0
	v_mov_b32_e32 v98, v0
	v_mov_b32_e32 v99, v0
	v_mov_b32_e32 v120, v0
	v_mov_b32_e32 v121, v0
	v_mov_b32_e32 v122, v0
	v_mov_b32_e32 v123, v0
	v_mov_b32_e32 v100, v0
	v_mov_b32_e32 v101, v0
	v_mov_b32_e32 v102, v0
	v_mov_b32_e32 v103, v0
	v_mov_b32_e32 v124, v0
	v_mov_b32_e32 v125, v0
	v_mov_b32_e32 v126, v0
	v_mov_b32_e32 v127, v0
	.p2alignl 7, 3212836864

.LBB0_985:
	s_ashr_i32 s13, s12, 31
	v_cmp_lt_i64_e32 vcc, s[0:1], v[142:143]
	s_lshl_b64 s[0:1], s[12:13], 20
	s_add_u32 s14, s38, s0
	s_addc_u32 s15, s39, s1
	s_and_b64 s[0:1], vcc, exec
	s_cselect_b32 s0, s15, s37
	s_cselect_b32 s1, s14, s36
	s_ashr_i32 s11, s10, 31
	s_lshl_b64 s[4:5], s[10:11], 20
	s_add_u32 s16, s62, s4
	s_addc_u32 s17, s63, s5
	s_and_b64 s[4:5], vcc, exec
	s_cselect_b32 s11, s17, s51
	s_cselect_b32 s13, s16, s50
	s_add_u32 s60, s36, 0x80080
	s_addc_u32 s61, s37, 0
	s_add_u32 s36, s50, 0x100
	v_mov_b32_e32 v0, 0
	s_addc_u32 s37, s51, 0
	s_mov_b32 s64, -2
	v_mov_b32_e32 v1, v0
	v_mov_b32_e32 v2, v0
	v_mov_b32_e32 v3, v0
	v_mov_b32_e32 v4, v0
	v_mov_b32_e32 v5, v0
	v_mov_b32_e32 v6, v0
	v_mov_b32_e32 v7, v0
	v_mov_b32_e32 v16, v0
	v_mov_b32_e32 v17, v0
	v_mov_b32_e32 v18, v0
	v_mov_b32_e32 v19, v0
	v_mov_b32_e32 v20, v0
	v_mov_b32_e32 v21, v0
	v_mov_b32_e32 v22, v0
	v_mov_b32_e32 v23, v0
	v_mov_b32_e32 v32, v0
	v_mov_b32_e32 v33, v0
	v_mov_b32_e32 v34, v0
	v_mov_b32_e32 v35, v0
	v_mov_b32_e32 v36, v0
	v_mov_b32_e32 v37, v0
	v_mov_b32_e32 v38, v0
	v_mov_b32_e32 v39, v0
	v_mov_b32_e32 v48, v0
	v_mov_b32_e32 v49, v0
	v_mov_b32_e32 v50, v0
	v_mov_b32_e32 v51, v0
	v_mov_b32_e32 v52, v0
	v_mov_b32_e32 v53, v0
	v_mov_b32_e32 v54, v0
	v_mov_b32_e32 v55, v0
	v_mov_b32_e32 v8, v0
	v_mov_b32_e32 v9, v0
	v_mov_b32_e32 v10, v0
	v_mov_b32_e32 v11, v0
	v_mov_b32_e32 v12, v0
	v_mov_b32_e32 v13, v0
	v_mov_b32_e32 v14, v0
	v_mov_b32_e32 v15, v0
	v_mov_b32_e32 v24, v0
	v_mov_b32_e32 v25, v0
	v_mov_b32_e32 v26, v0
	v_mov_b32_e32 v27, v0
	v_mov_b32_e32 v28, v0
	v_mov_b32_e32 v29, v0
	v_mov_b32_e32 v30, v0
	v_mov_b32_e32 v31, v0
	v_mov_b32_e32 v40, v0
	v_mov_b32_e32 v41, v0
	v_mov_b32_e32 v42, v0
	v_mov_b32_e32 v43, v0
	v_mov_b32_e32 v44, v0
	v_mov_b32_e32 v45, v0
	v_mov_b32_e32 v46, v0
	v_mov_b32_e32 v47, v0
	v_mov_b32_e32 v56, v0
	v_mov_b32_e32 v57, v0
	v_mov_b32_e32 v58, v0
	v_mov_b32_e32 v59, v0
	v_mov_b32_e32 v60, v0
	v_mov_b32_e32 v61, v0
	v_mov_b32_e32 v62, v0
	v_mov_b32_e32 v63, v0
	v_mov_b32_e32 v64, v0
	v_mov_b32_e32 v65, v0
	v_mov_b32_e32 v66, v0
	v_mov_b32_e32 v67, v0
	v_mov_b32_e32 v68, v0
	v_mov_b32_e32 v69, v0
	v_mov_b32_e32 v70, v0
	v_mov_b32_e32 v71, v0
	v_mov_b32_e32 v80, v0
	v_mov_b32_e32 v81, v0
	v_mov_b32_e32 v82, v0
	v_mov_b32_e32 v83, v0
	v_mov_b32_e32 v84, v0
	v_mov_b32_e32 v85, v0
	v_mov_b32_e32 v86, v0
	v_mov_b32_e32 v87, v0
	v_mov_b32_e32 v96, v0
	v_mov_b32_e32 v97, v0
	v_mov_b32_e32 v98, v0
	v_mov_b32_e32 v99, v0
	v_mov_b32_e32 v100, v0
	v_mov_b32_e32 v101, v0
	v_mov_b32_e32 v102, v0
	v_mov_b32_e32 v103, v0
	v_mov_b32_e32 v112, v0
	v_mov_b32_e32 v113, v0
	v_mov_b32_e32 v114, v0
	v_mov_b32_e32 v115, v0
	v_mov_b32_e32 v116, v0
	v_mov_b32_e32 v117, v0
	v_mov_b32_e32 v118, v0
	v_mov_b32_e32 v119, v0
	v_mov_b32_e32 v72, v0
	v_mov_b32_e32 v73, v0
	v_mov_b32_e32 v74, v0
	v_mov_b32_e32 v75, v0
	v_mov_b32_e32 v76, v0
	v_mov_b32_e32 v77, v0
	v_mov_b32_e32 v78, v0
	v_mov_b32_e32 v79, v0
	v_mov_b32_e32 v88, v0
	v_mov_b32_e32 v89, v0
	v_mov_b32_e32 v90, v0
	v_mov_b32_e32 v91, v0
	v_mov_b32_e32 v92, v0
	v_mov_b32_e32 v93, v0
	v_mov_b32_e32 v94, v0
	v_mov_b32_e32 v95, v0
	v_mov_b32_e32 v104, v0
	v_mov_b32_e32 v105, v0
	v_mov_b32_e32 v106, v0
	v_mov_b32_e32 v107, v0
	v_mov_b32_e32 v108, v0
	v_mov_b32_e32 v109, v0
	v_mov_b32_e32 v110, v0
	v_mov_b32_e32 v111, v0
	v_mov_b32_e32 v120, v0
	v_mov_b32_e32 v121, v0
	v_mov_b32_e32 v122, v0
	v_mov_b32_e32 v123, v0
	v_mov_b32_e32 v124, v0
	v_mov_b32_e32 v125, v0
	v_mov_b32_e32 v126, v0
	v_mov_b32_e32 v127, v0
	.p2alignl 7, 3212836864

.LBB0_1097:
	s_add_u32 s0, s64, 0x100
	v_mov_b32_e32 v0, 0
	s_addc_u32 s1, s65, 0
	s_mov_b32 s76, -2
	v_mov_b32_e32 v1, v0
	v_mov_b32_e32 v2, v0
	v_mov_b32_e32 v3, v0
	v_mov_b32_e32 v16, v0
	v_mov_b32_e32 v17, v0
	v_mov_b32_e32 v18, v0
	v_mov_b32_e32 v19, v0
	v_mov_b32_e32 v4, v0
	v_mov_b32_e32 v5, v0
	v_mov_b32_e32 v6, v0
	v_mov_b32_e32 v7, v0
	v_mov_b32_e32 v20, v0
	v_mov_b32_e32 v21, v0
	v_mov_b32_e32 v22, v0
	v_mov_b32_e32 v23, v0
	v_mov_b32_e32 v8, v0
	v_mov_b32_e32 v9, v0
	v_mov_b32_e32 v10, v0
	v_mov_b32_e32 v11, v0
	v_mov_b32_e32 v24, v0
	v_mov_b32_e32 v25, v0
	v_mov_b32_e32 v26, v0
	v_mov_b32_e32 v27, v0
	v_mov_b32_e32 v12, v0
	v_mov_b32_e32 v13, v0
	v_mov_b32_e32 v14, v0
	v_mov_b32_e32 v15, v0
	v_mov_b32_e32 v32, v0
	v_mov_b32_e32 v33, v0
	v_mov_b32_e32 v34, v0
	v_mov_b32_e32 v35, v0
	v_mov_b32_e32 v52, v0
	v_mov_b32_e32 v53, v0
	v_mov_b32_e32 v54, v0
	v_mov_b32_e32 v55, v0
	v_mov_b32_e32 v80, v0
	v_mov_b32_e32 v81, v0
	v_mov_b32_e32 v82, v0
	v_mov_b32_e32 v83, v0
	v_mov_b32_e32 v60, v0
	v_mov_b32_e32 v61, v0
	v_mov_b32_e32 v62, v0
	v_mov_b32_e32 v63, v0
	v_mov_b32_e32 v88, v0
	v_mov_b32_e32 v89, v0
	v_mov_b32_e32 v90, v0
	v_mov_b32_e32 v91, v0
	v_mov_b32_e32 v68, v0
	v_mov_b32_e32 v69, v0
	v_mov_b32_e32 v70, v0
	v_mov_b32_e32 v71, v0
	v_mov_b32_e32 v104, v0
	v_mov_b32_e32 v105, v0
	v_mov_b32_e32 v106, v0
	v_mov_b32_e32 v107, v0
	v_mov_b32_e32 v76, v0
	v_mov_b32_e32 v77, v0
	v_mov_b32_e32 v78, v0
	v_mov_b32_e32 v79, v0
	v_mov_b32_e32 v108, v0
	v_mov_b32_e32 v109, v0
	v_mov_b32_e32 v110, v0
	v_mov_b32_e32 v111, v0
	v_mov_b32_e32 v28, v0
	v_mov_b32_e32 v29, v0
	v_mov_b32_e32 v30, v0
	v_mov_b32_e32 v31, v0
	v_mov_b32_e32 v48, v0
	v_mov_b32_e32 v49, v0
	v_mov_b32_e32 v50, v0
	v_mov_b32_e32 v51, v0
	v_mov_b32_e32 v36, v0
	v_mov_b32_e32 v37, v0
	v_mov_b32_e32 v38, v0
	v_mov_b32_e32 v39, v0
	v_mov_b32_e32 v56, v0
	v_mov_b32_e32 v57, v0
	v_mov_b32_e32 v58, v0
	v_mov_b32_e32 v59, v0
	v_mov_b32_e32 v40, v0
	v_mov_b32_e32 v41, v0
	v_mov_b32_e32 v42, v0
	v_mov_b32_e32 v43, v0
	v_mov_b32_e32 v64, v0
	v_mov_b32_e32 v65, v0
	v_mov_b32_e32 v66, v0
	v_mov_b32_e32 v67, v0
	v_mov_b32_e32 v44, v0
	v_mov_b32_e32 v45, v0
	v_mov_b32_e32 v46, v0
	v_mov_b32_e32 v47, v0
	v_mov_b32_e32 v72, v0
	v_mov_b32_e32 v73, v0
	v_mov_b32_e32 v74, v0
	v_mov_b32_e32 v75, v0
	v_mov_b32_e32 v84, v0
	v_mov_b32_e32 v85, v0
	v_mov_b32_e32 v86, v0
	v_mov_b32_e32 v87, v0
	v_mov_b32_e32 v112, v0
	v_mov_b32_e32 v113, v0
	v_mov_b32_e32 v114, v0
	v_mov_b32_e32 v115, v0
	v_mov_b32_e32 v92, v0
	v_mov_b32_e32 v93, v0
	v_mov_b32_e32 v94, v0
	v_mov_b32_e32 v95, v0
	v_mov_b32_e32 v116, v0
	v_mov_b32_e32 v117, v0
	v_mov_b32_e32 v118, v0
	v_mov_b32_e32 v119, v0
	v_mov_b32_e32 v96, v0
	v_mov_b32_e32 v97, v0
	v_mov_b32_e32 v98, v0
	v_mov_b32_e32 v99, v0
	v_mov_b32_e32 v120, v0
	v_mov_b32_e32 v121, v0
	v_mov_b32_e32 v122, v0
	v_mov_b32_e32 v123, v0
	v_mov_b32_e32 v100, v0
	v_mov_b32_e32 v101, v0
	v_mov_b32_e32 v102, v0
	v_mov_b32_e32 v103, v0
	v_mov_b32_e32 v124, v0
	v_mov_b32_e32 v125, v0
	v_mov_b32_e32 v126, v0
	v_mov_b32_e32 v127, v0
	.p2alignl 7, 3212836864

.LBB0_1233:
	s_ashr_i32 s15, s14, 31
	v_cmp_lt_i64_e32 vcc, s[0:1], v[148:149]
	s_lshl_b64 s[0:1], s[14:15], 20
	s_add_u32 s16, s38, s0
	s_addc_u32 s17, s39, s1
	s_and_b64 s[0:1], vcc, exec
	s_cselect_b32 s0, s17, s37
	s_cselect_b32 s1, s16, s36
	s_ashr_i32 s13, s12, 31
	s_lshl_b64 s[4:5], s[12:13], 20
	s_add_u32 s18, s54, s4
	s_addc_u32 s19, s55, s5
	s_and_b64 s[4:5], vcc, exec
	s_cselect_b32 s13, s19, s59
	s_cselect_b32 s15, s18, s58
	s_add_u32 s46, s36, 0x80080
	s_addc_u32 s47, s37, 0
	s_add_u32 s36, s58, 0x100
	v_mov_b32_e32 v0, 0
	s_addc_u32 s37, s59, 0
	s_mov_b32 s64, -2
	v_mov_b32_e32 v1, v0
	v_mov_b32_e32 v2, v0
	v_mov_b32_e32 v3, v0
	v_mov_b32_e32 v4, v0
	v_mov_b32_e32 v5, v0
	v_mov_b32_e32 v6, v0
	v_mov_b32_e32 v7, v0
	v_mov_b32_e32 v8, v0
	v_mov_b32_e32 v9, v0
	v_mov_b32_e32 v10, v0
	v_mov_b32_e32 v11, v0
	v_mov_b32_e32 v12, v0
	v_mov_b32_e32 v13, v0
	v_mov_b32_e32 v14, v0
	v_mov_b32_e32 v15, v0
	v_mov_b32_e32 v16, v0
	v_mov_b32_e32 v17, v0
	v_mov_b32_e32 v18, v0
	v_mov_b32_e32 v19, v0
	v_mov_b32_e32 v20, v0
	v_mov_b32_e32 v21, v0
	v_mov_b32_e32 v22, v0
	v_mov_b32_e32 v23, v0
	v_mov_b32_e32 v24, v0
	v_mov_b32_e32 v25, v0
	v_mov_b32_e32 v26, v0
	v_mov_b32_e32 v27, v0
	v_mov_b32_e32 v28, v0
	v_mov_b32_e32 v29, v0
	v_mov_b32_e32 v30, v0
	v_mov_b32_e32 v31, v0
	v_mov_b32_e32 v56, v0
	v_mov_b32_e32 v57, v0
	v_mov_b32_e32 v58, v0
	v_mov_b32_e32 v59, v0
	v_mov_b32_e32 v60, v0
	v_mov_b32_e32 v61, v0
	v_mov_b32_e32 v62, v0
	v_mov_b32_e32 v63, v0
	v_mov_b32_e32 v72, v0
	v_mov_b32_e32 v73, v0
	v_mov_b32_e32 v74, v0
	v_mov_b32_e32 v75, v0
	v_mov_b32_e32 v76, v0
	v_mov_b32_e32 v77, v0
	v_mov_b32_e32 v78, v0
	v_mov_b32_e32 v79, v0
	v_mov_b32_e32 v80, v0
	v_mov_b32_e32 v81, v0
	v_mov_b32_e32 v82, v0
	v_mov_b32_e32 v83, v0
	v_mov_b32_e32 v84, v0
	v_mov_b32_e32 v85, v0
	v_mov_b32_e32 v86, v0
	v_mov_b32_e32 v87, v0
	v_mov_b32_e32 v88, v0
	v_mov_b32_e32 v89, v0
	v_mov_b32_e32 v90, v0
	v_mov_b32_e32 v91, v0
	v_mov_b32_e32 v92, v0
	v_mov_b32_e32 v93, v0
	v_mov_b32_e32 v94, v0
	v_mov_b32_e32 v95, v0
	v_mov_b32_e32 v32, v0
	v_mov_b32_e32 v33, v0
	v_mov_b32_e32 v34, v0
	v_mov_b32_e32 v35, v0
	v_mov_b32_e32 v36, v0
	v_mov_b32_e32 v37, v0
	v_mov_b32_e32 v38, v0
	v_mov_b32_e32 v39, v0
	v_mov_b32_e32 v40, v0
	v_mov_b32_e32 v41, v0
	v_mov_b32_e32 v42, v0
	v_mov_b32_e32 v43, v0
	v_mov_b32_e32 v44, v0
	v_mov_b32_e32 v45, v0
	v_mov_b32_e32 v46, v0
	v_mov_b32_e32 v47, v0
	v_mov_b32_e32 v48, v0
	v_mov_b32_e32 v49, v0
	v_mov_b32_e32 v50, v0
	v_mov_b32_e32 v51, v0
	v_mov_b32_e32 v52, v0
	v_mov_b32_e32 v53, v0
	v_mov_b32_e32 v54, v0
	v_mov_b32_e32 v55, v0
	v_mov_b32_e32 v64, v0
	v_mov_b32_e32 v65, v0
	v_mov_b32_e32 v66, v0
	v_mov_b32_e32 v67, v0
	v_mov_b32_e32 v68, v0
	v_mov_b32_e32 v69, v0
	v_mov_b32_e32 v70, v0
	v_mov_b32_e32 v71, v0
	v_mov_b32_e32 v96, v0
	v_mov_b32_e32 v97, v0
	v_mov_b32_e32 v98, v0
	v_mov_b32_e32 v99, v0
	v_mov_b32_e32 v100, v0
	v_mov_b32_e32 v101, v0
	v_mov_b32_e32 v102, v0
	v_mov_b32_e32 v103, v0
	v_mov_b32_e32 v104, v0
	v_mov_b32_e32 v105, v0
	v_mov_b32_e32 v106, v0
	v_mov_b32_e32 v107, v0
	v_mov_b32_e32 v108, v0
	v_mov_b32_e32 v109, v0
	v_mov_b32_e32 v110, v0
	v_mov_b32_e32 v111, v0
	v_mov_b32_e32 v112, v0
	v_mov_b32_e32 v113, v0
	v_mov_b32_e32 v114, v0
	v_mov_b32_e32 v115, v0
	v_mov_b32_e32 v116, v0
	v_mov_b32_e32 v117, v0
	v_mov_b32_e32 v118, v0
	v_mov_b32_e32 v119, v0
	v_mov_b32_e32 v120, v0
	v_mov_b32_e32 v121, v0
	v_mov_b32_e32 v122, v0
	v_mov_b32_e32 v123, v0
	v_mov_b32_e32 v124, v0
	v_mov_b32_e32 v125, v0
	v_mov_b32_e32 v126, v0
	v_mov_b32_e32 v127, v0
	.p2alignl 7, 3212836864

.LBB0_1532:
	s_ashr_i32 s61, s60, 31
	v_cmp_lt_i64_e32 vcc, s[0:1], v[146:147]
	s_lshl_b64 s[0:1], s[60:61], 20
	s_add_u32 s62, s38, s0
	s_addc_u32 s63, s39, s1
	s_and_b64 s[0:1], vcc, exec
	s_cselect_b32 s0, s63, s9
	s_cselect_b32 s1, s62, s8
	s_ashr_i32 s59, s58, 31
	s_lshl_b64 s[4:5], s[58:59], 20
	v_readlane_b32 s42, v255, 26
	v_readlane_b32 s43, v255, 27
	s_add_u32 s64, s42, s4
	s_addc_u32 s65, s43, s5
	s_and_b64 s[4:5], vcc, exec
	s_cselect_b32 s59, s65, s69
	s_cselect_b32 s61, s64, s68
	s_add_u32 s76, s68, 0x100
	v_mov_b32_e32 v0, 0
	s_addc_u32 s77, s69, 0
	s_mov_b32 s78, -2
	v_mov_b32_e32 v1, v0
	v_mov_b32_e32 v2, v0
	v_mov_b32_e32 v3, v0
	v_mov_b32_e32 v32, v0
	v_mov_b32_e32 v33, v0
	v_mov_b32_e32 v34, v0
	v_mov_b32_e32 v35, v0
	v_mov_b32_e32 v4, v0
	v_mov_b32_e32 v5, v0
	v_mov_b32_e32 v6, v0
	v_mov_b32_e32 v7, v0
	v_mov_b32_e32 v36, v0
	v_mov_b32_e32 v37, v0
	v_mov_b32_e32 v38, v0
	v_mov_b32_e32 v39, v0
	v_mov_b32_e32 v8, v0
	v_mov_b32_e32 v9, v0
	v_mov_b32_e32 v10, v0
	v_mov_b32_e32 v11, v0
	v_mov_b32_e32 v40, v0
	v_mov_b32_e32 v41, v0
	v_mov_b32_e32 v42, v0
	v_mov_b32_e32 v43, v0
	v_mov_b32_e32 v12, v0
	v_mov_b32_e32 v13, v0
	v_mov_b32_e32 v14, v0
	v_mov_b32_e32 v15, v0
	v_mov_b32_e32 v44, v0
	v_mov_b32_e32 v45, v0
	v_mov_b32_e32 v46, v0
	v_mov_b32_e32 v47, v0
	v_mov_b32_e32 v64, v0
	v_mov_b32_e32 v65, v0
	v_mov_b32_e32 v66, v0
	v_mov_b32_e32 v67, v0
	v_mov_b32_e32 v96, v0
	v_mov_b32_e32 v97, v0
	v_mov_b32_e32 v98, v0
	v_mov_b32_e32 v99, v0
	v_mov_b32_e32 v68, v0
	v_mov_b32_e32 v69, v0
	v_mov_b32_e32 v70, v0
	v_mov_b32_e32 v71, v0
	v_mov_b32_e32 v100, v0
	v_mov_b32_e32 v101, v0
	v_mov_b32_e32 v102, v0
	v_mov_b32_e32 v103, v0
	v_mov_b32_e32 v72, v0
	v_mov_b32_e32 v73, v0
	v_mov_b32_e32 v74, v0
	v_mov_b32_e32 v75, v0
	v_mov_b32_e32 v104, v0
	v_mov_b32_e32 v105, v0
	v_mov_b32_e32 v106, v0
	v_mov_b32_e32 v107, v0
	v_mov_b32_e32 v76, v0
	v_mov_b32_e32 v77, v0
	v_mov_b32_e32 v78, v0
	v_mov_b32_e32 v79, v0
	v_mov_b32_e32 v108, v0
	v_mov_b32_e32 v109, v0
	v_mov_b32_e32 v110, v0
	v_mov_b32_e32 v111, v0
	v_mov_b32_e32 v16, v0
	v_mov_b32_e32 v17, v0
	v_mov_b32_e32 v18, v0
	v_mov_b32_e32 v19, v0
	v_mov_b32_e32 v48, v0
	v_mov_b32_e32 v49, v0
	v_mov_b32_e32 v50, v0
	v_mov_b32_e32 v51, v0
	v_mov_b32_e32 v20, v0
	v_mov_b32_e32 v21, v0
	v_mov_b32_e32 v22, v0
	v_mov_b32_e32 v23, v0
	v_mov_b32_e32 v52, v0
	v_mov_b32_e32 v53, v0
	v_mov_b32_e32 v54, v0
	v_mov_b32_e32 v55, v0
	v_mov_b32_e32 v24, v0
	v_mov_b32_e32 v25, v0
	v_mov_b32_e32 v26, v0
	v_mov_b32_e32 v27, v0
	v_mov_b32_e32 v56, v0
	v_mov_b32_e32 v57, v0
	v_mov_b32_e32 v58, v0
	v_mov_b32_e32 v59, v0
	v_mov_b32_e32 v28, v0
	v_mov_b32_e32 v29, v0
	v_mov_b32_e32 v30, v0
	v_mov_b32_e32 v31, v0
	v_mov_b32_e32 v60, v0
	v_mov_b32_e32 v61, v0
	v_mov_b32_e32 v62, v0
	v_mov_b32_e32 v63, v0
	v_mov_b32_e32 v80, v0
	v_mov_b32_e32 v81, v0
	v_mov_b32_e32 v82, v0
	v_mov_b32_e32 v83, v0
	v_mov_b32_e32 v112, v0
	v_mov_b32_e32 v113, v0
	v_mov_b32_e32 v114, v0
	v_mov_b32_e32 v115, v0
	v_mov_b32_e32 v84, v0
	v_mov_b32_e32 v85, v0
	v_mov_b32_e32 v86, v0
	v_mov_b32_e32 v87, v0
	v_mov_b32_e32 v116, v0
	v_mov_b32_e32 v117, v0
	v_mov_b32_e32 v118, v0
	v_mov_b32_e32 v119, v0
	v_mov_b32_e32 v88, v0
	v_mov_b32_e32 v89, v0
	v_mov_b32_e32 v90, v0
	v_mov_b32_e32 v91, v0
	v_mov_b32_e32 v120, v0
	v_mov_b32_e32 v121, v0
	v_mov_b32_e32 v122, v0
	v_mov_b32_e32 v123, v0
	v_mov_b32_e32 v92, v0
	v_mov_b32_e32 v93, v0
	v_mov_b32_e32 v94, v0
	v_mov_b32_e32 v95, v0
	v_mov_b32_e32 v124, v0
	v_mov_b32_e32 v125, v0
	v_mov_b32_e32 v126, v0
	v_mov_b32_e32 v127, v0
	.p2alignl 7, 3212836864

.LBB0_1675:
	s_ashr_i32 s13, s12, 31
	v_cmp_lt_i64_e32 vcc, s[0:1], v[140:141]
	s_lshl_b64 s[0:1], s[12:13], 20
	s_add_u32 s14, s38, s0
	s_addc_u32 s15, s39, s1
	s_and_b64 s[0:1], vcc, exec
	s_cselect_b32 s0, s15, s21
	s_cselect_b32 s1, s14, s20
	s_ashr_i32 s11, s10, 31
	s_lshl_b64 s[4:5], s[10:11], 20
	s_add_u32 s16, s56, s4
	s_addc_u32 s17, s57, s5
	s_and_b64 s[4:5], vcc, exec
	s_cselect_b32 s11, s17, s45
	s_cselect_b32 s13, s16, s44
	s_add_u32 s20, s20, 0x80080
	s_addc_u32 s21, s21, 0
	s_add_u32 s51, s44, 0x100
	v_mov_b32_e32 v0, 0
	s_addc_u32 s52, s45, 0
	s_mov_b32 s53, -2
	v_mov_b32_e32 v1, v0
	v_mov_b32_e32 v2, v0
	v_mov_b32_e32 v3, v0
	v_mov_b32_e32 v4, v0
	v_mov_b32_e32 v5, v0
	v_mov_b32_e32 v6, v0
	v_mov_b32_e32 v7, v0
	v_mov_b32_e32 v16, v0
	v_mov_b32_e32 v17, v0
	v_mov_b32_e32 v18, v0
	v_mov_b32_e32 v19, v0
	v_mov_b32_e32 v20, v0
	v_mov_b32_e32 v21, v0
	v_mov_b32_e32 v22, v0
	v_mov_b32_e32 v23, v0
	v_mov_b32_e32 v32, v0
	v_mov_b32_e32 v33, v0
	v_mov_b32_e32 v34, v0
	v_mov_b32_e32 v35, v0
	v_mov_b32_e32 v36, v0
	v_mov_b32_e32 v37, v0
	v_mov_b32_e32 v38, v0
	v_mov_b32_e32 v39, v0
	v_mov_b32_e32 v48, v0
	v_mov_b32_e32 v49, v0
	v_mov_b32_e32 v50, v0
	v_mov_b32_e32 v51, v0
	v_mov_b32_e32 v52, v0
	v_mov_b32_e32 v53, v0
	v_mov_b32_e32 v54, v0
	v_mov_b32_e32 v55, v0
	v_mov_b32_e32 v8, v0
	v_mov_b32_e32 v9, v0
	v_mov_b32_e32 v10, v0
	v_mov_b32_e32 v11, v0
	v_mov_b32_e32 v12, v0
	v_mov_b32_e32 v13, v0
	v_mov_b32_e32 v14, v0
	v_mov_b32_e32 v15, v0
	v_mov_b32_e32 v24, v0
	v_mov_b32_e32 v25, v0
	v_mov_b32_e32 v26, v0
	v_mov_b32_e32 v27, v0
	v_mov_b32_e32 v28, v0
	v_mov_b32_e32 v29, v0
	v_mov_b32_e32 v30, v0
	v_mov_b32_e32 v31, v0
	v_mov_b32_e32 v40, v0
	v_mov_b32_e32 v41, v0
	v_mov_b32_e32 v42, v0
	v_mov_b32_e32 v43, v0
	v_mov_b32_e32 v44, v0
	v_mov_b32_e32 v45, v0
	v_mov_b32_e32 v46, v0
	v_mov_b32_e32 v47, v0
	v_mov_b32_e32 v56, v0
	v_mov_b32_e32 v57, v0
	v_mov_b32_e32 v58, v0
	v_mov_b32_e32 v59, v0
	v_mov_b32_e32 v60, v0
	v_mov_b32_e32 v61, v0
	v_mov_b32_e32 v62, v0
	v_mov_b32_e32 v63, v0
	v_mov_b32_e32 v64, v0
	v_mov_b32_e32 v65, v0
	v_mov_b32_e32 v66, v0
	v_mov_b32_e32 v67, v0
	v_mov_b32_e32 v68, v0
	v_mov_b32_e32 v69, v0
	v_mov_b32_e32 v70, v0
	v_mov_b32_e32 v71, v0
	v_mov_b32_e32 v80, v0
	v_mov_b32_e32 v81, v0
	v_mov_b32_e32 v82, v0
	v_mov_b32_e32 v83, v0
	v_mov_b32_e32 v84, v0
	v_mov_b32_e32 v85, v0
	v_mov_b32_e32 v86, v0
	v_mov_b32_e32 v87, v0
	v_mov_b32_e32 v96, v0
	v_mov_b32_e32 v97, v0
	v_mov_b32_e32 v98, v0
	v_mov_b32_e32 v99, v0
	v_mov_b32_e32 v100, v0
	v_mov_b32_e32 v101, v0
	v_mov_b32_e32 v102, v0
	v_mov_b32_e32 v103, v0
	v_mov_b32_e32 v112, v0
	v_mov_b32_e32 v113, v0
	v_mov_b32_e32 v114, v0
	v_mov_b32_e32 v115, v0
	v_mov_b32_e32 v116, v0
	v_mov_b32_e32 v117, v0
	v_mov_b32_e32 v118, v0
	v_mov_b32_e32 v119, v0
	v_mov_b32_e32 v72, v0
	v_mov_b32_e32 v73, v0
	v_mov_b32_e32 v74, v0
	v_mov_b32_e32 v75, v0
	v_mov_b32_e32 v76, v0
	v_mov_b32_e32 v77, v0
	v_mov_b32_e32 v78, v0
	v_mov_b32_e32 v79, v0
	v_mov_b32_e32 v88, v0
	v_mov_b32_e32 v89, v0
	v_mov_b32_e32 v90, v0
	v_mov_b32_e32 v91, v0
	v_mov_b32_e32 v92, v0
	v_mov_b32_e32 v93, v0
	v_mov_b32_e32 v94, v0
	v_mov_b32_e32 v95, v0
	v_mov_b32_e32 v104, v0
	v_mov_b32_e32 v105, v0
	v_mov_b32_e32 v106, v0
	v_mov_b32_e32 v107, v0
	v_mov_b32_e32 v108, v0
	v_mov_b32_e32 v109, v0
	v_mov_b32_e32 v110, v0
	v_mov_b32_e32 v111, v0
	v_mov_b32_e32 v120, v0
	v_mov_b32_e32 v121, v0
	v_mov_b32_e32 v122, v0
	v_mov_b32_e32 v123, v0
	v_mov_b32_e32 v124, v0
	v_mov_b32_e32 v125, v0
	v_mov_b32_e32 v126, v0
	v_mov_b32_e32 v127, v0
	.p2alignl 7, 3212836864

.LBB0_1748:
	s_add_u32 s0, s44, 0x100
	v_mov_b32_e32 v0, 0
	s_addc_u32 s1, s45, 0
	s_mov_b32 s61, -2
	v_mov_b32_e32 v1, v0
	v_mov_b32_e32 v2, v0
	v_mov_b32_e32 v3, v0
	v_mov_b32_e32 v16, v0
	v_mov_b32_e32 v17, v0
	v_mov_b32_e32 v18, v0
	v_mov_b32_e32 v19, v0
	v_mov_b32_e32 v4, v0
	v_mov_b32_e32 v5, v0
	v_mov_b32_e32 v6, v0
	v_mov_b32_e32 v7, v0
	v_mov_b32_e32 v20, v0
	v_mov_b32_e32 v21, v0
	v_mov_b32_e32 v22, v0
	v_mov_b32_e32 v23, v0
	v_mov_b32_e32 v8, v0
	v_mov_b32_e32 v9, v0
	v_mov_b32_e32 v10, v0
	v_mov_b32_e32 v11, v0
	v_mov_b32_e32 v24, v0
	v_mov_b32_e32 v25, v0
	v_mov_b32_e32 v26, v0
	v_mov_b32_e32 v27, v0
	v_mov_b32_e32 v12, v0
	v_mov_b32_e32 v13, v0
	v_mov_b32_e32 v14, v0
	v_mov_b32_e32 v15, v0
	v_mov_b32_e32 v32, v0
	v_mov_b32_e32 v33, v0
	v_mov_b32_e32 v34, v0
	v_mov_b32_e32 v35, v0
	v_mov_b32_e32 v52, v0
	v_mov_b32_e32 v53, v0
	v_mov_b32_e32 v54, v0
	v_mov_b32_e32 v55, v0
	v_mov_b32_e32 v80, v0
	v_mov_b32_e32 v81, v0
	v_mov_b32_e32 v82, v0
	v_mov_b32_e32 v83, v0
	v_mov_b32_e32 v60, v0
	v_mov_b32_e32 v61, v0
	v_mov_b32_e32 v62, v0
	v_mov_b32_e32 v63, v0
	v_mov_b32_e32 v88, v0
	v_mov_b32_e32 v89, v0
	v_mov_b32_e32 v90, v0
	v_mov_b32_e32 v91, v0
	v_mov_b32_e32 v68, v0
	v_mov_b32_e32 v69, v0
	v_mov_b32_e32 v70, v0
	v_mov_b32_e32 v71, v0
	v_mov_b32_e32 v104, v0
	v_mov_b32_e32 v105, v0
	v_mov_b32_e32 v106, v0
	v_mov_b32_e32 v107, v0
	v_mov_b32_e32 v76, v0
	v_mov_b32_e32 v77, v0
	v_mov_b32_e32 v78, v0
	v_mov_b32_e32 v79, v0
	v_mov_b32_e32 v108, v0
	v_mov_b32_e32 v109, v0
	v_mov_b32_e32 v110, v0
	v_mov_b32_e32 v111, v0
	v_mov_b32_e32 v28, v0
	v_mov_b32_e32 v29, v0
	v_mov_b32_e32 v30, v0
	v_mov_b32_e32 v31, v0
	v_mov_b32_e32 v48, v0
	v_mov_b32_e32 v49, v0
	v_mov_b32_e32 v50, v0
	v_mov_b32_e32 v51, v0
	v_mov_b32_e32 v36, v0
	v_mov_b32_e32 v37, v0
	v_mov_b32_e32 v38, v0
	v_mov_b32_e32 v39, v0
	v_mov_b32_e32 v56, v0
	v_mov_b32_e32 v57, v0
	v_mov_b32_e32 v58, v0
	v_mov_b32_e32 v59, v0
	v_mov_b32_e32 v40, v0
	v_mov_b32_e32 v41, v0
	v_mov_b32_e32 v42, v0
	v_mov_b32_e32 v43, v0
	v_mov_b32_e32 v64, v0
	v_mov_b32_e32 v65, v0
	v_mov_b32_e32 v66, v0
	v_mov_b32_e32 v67, v0
	v_mov_b32_e32 v44, v0
	v_mov_b32_e32 v45, v0
	v_mov_b32_e32 v46, v0
	v_mov_b32_e32 v47, v0
	v_mov_b32_e32 v72, v0
	v_mov_b32_e32 v73, v0
	v_mov_b32_e32 v74, v0
	v_mov_b32_e32 v75, v0
	v_mov_b32_e32 v84, v0
	v_mov_b32_e32 v85, v0
	v_mov_b32_e32 v86, v0
	v_mov_b32_e32 v87, v0
	v_mov_b32_e32 v112, v0
	v_mov_b32_e32 v113, v0
	v_mov_b32_e32 v114, v0
	v_mov_b32_e32 v115, v0
	v_mov_b32_e32 v92, v0
	v_mov_b32_e32 v93, v0
	v_mov_b32_e32 v94, v0
	v_mov_b32_e32 v95, v0
	v_mov_b32_e32 v116, v0
	v_mov_b32_e32 v117, v0
	v_mov_b32_e32 v118, v0
	v_mov_b32_e32 v119, v0
	v_mov_b32_e32 v96, v0
	v_mov_b32_e32 v97, v0
	v_mov_b32_e32 v98, v0
	v_mov_b32_e32 v99, v0
	v_mov_b32_e32 v120, v0
	v_mov_b32_e32 v121, v0
	v_mov_b32_e32 v122, v0
	v_mov_b32_e32 v123, v0
	v_mov_b32_e32 v100, v0
	v_mov_b32_e32 v101, v0
	v_mov_b32_e32 v102, v0
	v_mov_b32_e32 v103, v0
	v_mov_b32_e32 v124, v0
	v_mov_b32_e32 v125, v0
	v_mov_b32_e32 v126, v0
	v_mov_b32_e32 v127, v0
	.p2alignl 7, 3212836864

	.text
	.p2alignl 7, 3212836864
	.fill 256, 4, 3212836864
